# retention K tile: XOR-swizzled 512B rows (conflict-free ds_read_b128 K fragments), 4 per-lane bases
# speedup vs baseline: 1.0111x; 1.0054x over previous
.LBB0_7:
	s_cmp_ge_i32 s28, s29
	s_cbranch_scc1 .LBB0_1029
	s_load_dwordx16 s[68:83], s[0:1], 0x0
	s_add_u32 s34, s0, 0x70
	s_addc_u32 s35, s1, 0
	v_lshrrev_b32_e32 v1, 20, v0
	v_lshrrev_b32_e32 v0, 10, v0
	s_waitcnt lgkmcnt(0)
	s_add_u32 s98, s70, 0x8000
	s_addc_u32 s99, s71, 0
	s_add_u32 s0, s70, 0x2000
	s_addc_u32 s1, s71, 0
	s_cmp_lg_u32 s30, 2
	s_cselect_b64 s[6:7], -1, 0
	v_writelane_b32 v253, s6, 10
	v_or_b32_e32 v0, v0, v1
	v_mov_b32_e32 v9, 0
	v_writelane_b32 v253, s7, 11
	v_mbcnt_lo_u32_b32 v1, -1, 0
	v_readlane_b32 s16, v253, 0
	v_readlane_b32 s22, v253, 6
	v_readlane_b32 s23, v253, 7
	s_add_u32 s6, s22, 0xc0200
	s_addc_u32 s7, s23, 0
	v_readlane_b32 s17, v253, 1
	v_readlane_b32 s18, v253, 2
	v_readlane_b32 s19, v253, 3
	v_readlane_b32 s20, v253, 4
	v_readlane_b32 s21, v253, 5
	v_writelane_b32 v253, s6, 12
	v_mov_b32_e32 v183, 0x358637bd
	v_mbcnt_hi_u32_b32 v184, -1, v1
	v_writelane_b32 v253, s7, 13
	s_add_u32 s6, s22, 0xc0400
	s_addc_u32 s7, s23, 0
	v_writelane_b32 v253, s6, 14
	v_mov_b32_e32 v185, 1
	v_mov_b32_e32 v186, 0x3d800000
	v_writelane_b32 v253, s7, 15
	s_add_u32 s6, s22, 0xc0500
	s_addc_u32 s7, s23, 0
	v_writelane_b32 v253, s6, 16
	v_mov_b64_e32 v[158:159], 0x300
	v_mov_b64_e32 v[160:161], 0x2ff
	v_writelane_b32 v253, s7, 17
	s_add_u32 s6, s22, 0xc0600
	s_addc_u32 s7, s23, 0
	v_writelane_b32 v253, s6, 18
	v_mov_b32_e32 v187, 0x3e0293ee
	v_mov_b64_e32 v[162:163], 0x100
	v_writelane_b32 v253, s7, 19
	s_add_u32 s6, s22, 0xc0700
	s_addc_u32 s7, s23, 0
	v_writelane_b32 v253, s6, 20
	v_mov_b64_e32 v[164:165], 0xff
	v_mov_b32_e32 v188, 0xff800000
	v_writelane_b32 v253, s7, 21
	s_add_u32 s6, s22, 0xc0800
	s_addc_u32 s7, s23, 0
	v_writelane_b32 v253, s6, 22
	v_mov_b64_e32 v[166:167], 0x580
	v_mov_b64_e32 v[168:169], 0x57f
	v_writelane_b32 v253, s7, 23
	s_add_u32 s6, s22, 0xc0900
	s_addc_u32 s7, s23, 0
	v_writelane_b32 v253, s6, 24
	v_mov_b32_e32 v224, v9
	v_mov_b32_e32 v225, v9
	v_writelane_b32 v253, s7, 25
	s_add_u32 s6, s22, 0xc0a00
	s_addc_u32 s7, s23, 0
	v_writelane_b32 v253, s6, 26
	s_movk_i32 s66, 0x2c00
	s_movk_i32 s67, 0x6000
	v_writelane_b32 v253, s7, 27
	s_add_u32 s6, s22, 0xc0b00
	s_addc_u32 s7, s23, 0
	v_writelane_b32 v253, s6, 28
	s_mov_b32 s64, 0xb000
	s_movk_i32 s65, 0x3000
	v_writelane_b32 v253, s7, 29
	s_add_u32 s6, s22, 0xc0c00
	s_addc_u32 s7, s23, 0
	v_writelane_b32 v253, s6, 30
	s_movk_i32 s96, 0x200
	s_movk_i32 s92, 0x220
	v_writelane_b32 v253, s7, 31
	s_add_u32 s6, s22, 0xc0d00
	s_addc_u32 s7, s23, 0
	v_writelane_b32 v253, s6, 32
	s_mov_b32 s93, 0x5040100
	s_movk_i32 s33, 0x110
	v_writelane_b32 v253, s7, 33
	s_add_u32 s6, s22, 0xc0e00
	s_addc_u32 s7, s23, 0
	v_writelane_b32 v253, s6, 34
	s_movk_i32 s84, 0x120
	s_flbit_i32_b32 s85, 0
	v_writelane_b32 v253, s7, 35
	s_add_u32 s6, s22, 0xc0f00
	s_addc_u32 s7, s23, 0
	v_writelane_b32 v253, s6, 36
	s_mov_b64 s[94:95], 0x80
	s_nop 0
	v_writelane_b32 v253, s7, 37
	s_add_u32 s6, s22, 0xc1000
	s_addc_u32 s7, s23, 0
	v_writelane_b32 v253, s6, 38
	s_nop 1
	v_writelane_b32 v253, s7, 39
	s_add_u32 s6, s22, 0xc1100
	s_addc_u32 s7, s23, 0
	v_writelane_b32 v253, s6, 40
	s_nop 1
	v_writelane_b32 v253, s7, 41
	s_add_u32 s6, s22, 0xc1200
	s_addc_u32 s7, s23, 0
	v_writelane_b32 v253, s6, 42
	s_nop 1
	v_writelane_b32 v253, s7, 43
	s_add_u32 s6, s22, 0xc1300
	s_addc_u32 s7, s23, 0
	v_writelane_b32 v253, s6, 44
	s_cmp_eq_u32 s12, 15
	s_nop 0
	v_writelane_b32 v253, s7, 45
	s_cselect_b64 s[6:7], -1, 0
	v_writelane_b32 v253, s6, 46
	s_cmp_eq_u32 s12, 14
	s_nop 0
	v_writelane_b32 v253, s7, 47
	s_cselect_b64 s[6:7], -1, 0
	v_writelane_b32 v253, s6, 48
	s_cmp_eq_u32 s12, 13
	s_nop 0
	v_writelane_b32 v253, s7, 49
	s_cselect_b64 s[6:7], -1, 0
	v_writelane_b32 v253, s6, 50
	s_cmp_eq_u32 s12, 12
	s_nop 0
	v_writelane_b32 v253, s7, 51
	s_cselect_b64 s[6:7], -1, 0
	v_writelane_b32 v253, s6, 52
	s_cmp_eq_u32 s12, 11
	s_nop 0
	v_writelane_b32 v253, s7, 53
	s_cselect_b64 s[6:7], -1, 0
	v_writelane_b32 v253, s6, 54
	s_cmp_eq_u32 s12, 10
	s_nop 0
	v_writelane_b32 v253, s7, 55
	s_cselect_b64 s[6:7], -1, 0
	v_writelane_b32 v253, s6, 56
	s_cmp_eq_u32 s12, 9
	s_nop 0
	v_writelane_b32 v253, s7, 57
	s_cselect_b64 s[6:7], -1, 0
	v_writelane_b32 v253, s6, 58
	s_cmp_eq_u32 s12, 8
	s_nop 0
	v_writelane_b32 v253, s7, 59
	s_cselect_b64 s[6:7], -1, 0
	v_writelane_b32 v253, s6, 60
	s_cmp_eq_u32 s12, 7
	s_nop 0
	v_writelane_b32 v253, s7, 61
	s_cselect_b64 s[6:7], -1, 0
	v_writelane_b32 v253, s6, 62
	s_cmp_eq_u32 s12, 6
	s_nop 0
	v_writelane_b32 v253, s7, 63
	s_cselect_b64 s[6:7], -1, 0
	v_writelane_b32 v254, s6, 0
	s_cmp_eq_u32 s12, 5
	s_nop 0
	v_writelane_b32 v254, s7, 1
	s_cselect_b64 s[6:7], -1, 0
	v_writelane_b32 v254, s6, 2
	s_cmp_eq_u32 s12, 4
	s_nop 0
	v_writelane_b32 v254, s7, 3
	s_cselect_b64 s[6:7], -1, 0
	v_writelane_b32 v254, s6, 4
	s_cmp_eq_u32 s12, 3
	s_nop 0
	v_writelane_b32 v254, s7, 5
	s_cselect_b64 s[6:7], -1, 0
	v_writelane_b32 v254, s6, 6
	s_cmp_eq_u32 s12, 2
	s_nop 0
	v_writelane_b32 v254, s7, 7
	s_cselect_b64 s[6:7], -1, 0
	v_writelane_b32 v254, s6, 8
	s_cmp_eq_u32 s12, 1
	s_nop 0
	v_writelane_b32 v254, s7, 9
	s_cselect_b64 s[6:7], -1, 0
	v_writelane_b32 v254, s6, 10
	s_cmp_eq_u32 s12, 0
	s_nop 0
	v_writelane_b32 v254, s7, 11
	s_cselect_b64 s[6:7], -1, 0
	s_lshl_b32 s3, s12, 8
	s_add_u32 s4, s4, s3
	v_writelane_b32 v254, s6, 12
	s_addc_u32 s3, s5, 0
	s_nop 0
	v_writelane_b32 v254, s7, 13
	s_add_u32 s6, s4, 0x1400
	s_addc_u32 s7, s3, 0
	v_writelane_b32 v254, s6, 14
	s_add_u32 s4, s4, 0x2400
	s_addc_u32 s5, s3, 0
	v_writelane_b32 v254, s7, 15
	v_writelane_b32 v254, s4, 16
	s_movk_i32 s3, 0x3ff
	v_and_or_b32 v0, v0, s3, v182
	v_writelane_b32 v254, s5, 17
	s_add_u32 s4, s22, 0xc3400
	s_addc_u32 s5, s23, 0
	v_writelane_b32 v254, s4, 18
	s_nop 1
	v_writelane_b32 v254, s5, 19
	s_add_u32 s4, s22, 0xc3500
	s_addc_u32 s5, s23, 0
	v_writelane_b32 v254, s4, 20
	s_add_u32 s3, s70, 0x78
	s_nop 0
	v_writelane_b32 v254, s5, 21
	v_writelane_b32 v254, s3, 22
	s_addc_u32 s3, s71, 0
	v_writelane_b32 v254, s3, 23
	s_add_u32 s3, s68, 0x1c00
	v_writelane_b32 v254, s3, 24
	s_addc_u32 s3, s69, 0
	v_writelane_b32 v254, s3, 25
	s_add_i32 s3, 0, 0x11800
	v_writelane_b32 v254, s3, 26
	s_add_i32 s4, 0, 0x23fc0
	v_writelane_b32 v254, s4, 27
	s_add_i32 s4, 0, 0x23fc4
	v_writelane_b32 v254, s4, 28
	v_cmp_eq_u32_e64 s[4:5], 0, v182
	s_add_i32 s97, 0, 0x10800
	s_mov_b32 s3, 0xff800000
	v_writelane_b32 v254, s4, 29
	s_mov_b32 s69, 0
	s_nop 0
	v_writelane_b32 v254, s5, 30
	v_cmp_eq_u32_e64 s[4:5], 0, v0
	s_nop 1
	v_writelane_b32 v254, s4, 31
	s_nop 1
	v_writelane_b32 v254, s5, 32
	v_writelane_b32 v254, s2, 33
	v_writelane_b32 v254, s34, 34
	s_nop 1
	v_writelane_b32 v254, s35, 35
	s_branch .LBB0_12

.LBB0_862:
	s_xor_b64 s[46:47], s[4:5], -1
	s_and_b64 s[4:5], s[4:5], exec
	v_mov_b32_e32 v20, v170
	s_cselect_b32 s9, s7, s8
	v_readfirstlane_b32 s4, v20
	s_ashr_i32 s4, s4, 2
	s_and_b32 s4, s4, -16
	v_and_b32_e32 v21, 15, v20
	s_add_i32 s4, s4, s9
	v_or_b32_e32 v172, s4, v21
	v_ashrrev_i32_e32 v173, 31, v172
	v_bfe_u32 v22, v20, 4, 2
	s_waitcnt lgkmcnt(0)
	v_lshlrev_b64 v[0:1], 14, v[172:173]
	v_lshl_add_u64 v[0:1], s[22:23], 0, v[0:1]
	v_lshlrev_b32_e32 v8, 4, v22
	v_lshl_add_u64 v[0:1], v[0:1], 0, v[8:9]
	v_mov_b32_e32 v16, v170
	global_load_dwordx4 v[102:105], v[0:1], off
	global_load_dwordx4 v[98:101], v[0:1], off offset:64
	global_load_dwordx4 v[94:97], v[0:1], off offset:128
	global_load_dwordx4 v[90:93], v[0:1], off offset:192
	global_load_dwordx4 v[86:89], v[0:1], off offset:256
	global_load_dwordx4 v[82:85], v[0:1], off offset:320
	global_load_dwordx4 v[78:81], v[0:1], off offset:384
	global_load_dwordx4 v[74:77], v[0:1], off offset:448
	v_mov_b32_e32 v23, v170
	v_lshlrev_b32_e32 v0, 4, v16
	v_and_b32_e32 v8, 0x1f0, v0
	v_lshl_add_u64 v[14:15], s[24:25], 0, v[8:9]
	v_lshrrev_b32_e32 v8, 5, v16
	v_lshlrev_b64 v[0:1], 14, v[8:9]
	v_lshl_add_u64 v[0:1], v[14:15], 0, v[0:1]
	v_add_u32_e32 v4, 0x200, v16
	global_load_dwordx4 v[0:3], v[0:1], off
	v_lshrrev_b32_e32 v8, 5, v4
	v_lshlrev_b64 v[4:5], 14, v[8:9]
	v_lshl_add_u64 v[4:5], v[14:15], 0, v[4:5]
	v_add_u32_e32 v8, 0x400, v16
	global_load_dwordx4 v[4:7], v[4:5], off
	v_lshrrev_b32_e32 v8, 5, v8
	v_lshlrev_b64 v[10:11], 14, v[8:9]
	v_lshl_add_u64 v[10:11], v[14:15], 0, v[10:11]
	v_add_u32_e32 v8, 0x600, v16
	global_load_dwordx4 v[10:13], v[10:11], off
	v_lshrrev_b32_e32 v8, 5, v8
	v_lshlrev_b64 v[16:17], 14, v[8:9]
	v_lshl_add_u64 v[14:15], v[14:15], 0, v[16:17]
	global_load_dwordx4 v[14:17], v[14:15], off
	v_lshlrev_b32_e32 v194, 2, v22
	v_lshlrev_b32_e32 v8, 4, v23
	v_and_b32_e32 v8, 0x1f0, v8
	v_lshrrev_b32_e32 v246, 1, v23
	v_and_b32_e32 v246, 0xf0, v246
	v_xor_b32_e32 v8, v8, v246
	v_add_u32_e32 v8, 0, v8
	v_lshrrev_b32_e32 v18, 5, v23
	v_mad_u64_u32 v[18:19], s[16:17], v18, s96, v[8:9]
	s_add_i32 s5, s9, 0x80
	v_readfirstlane_b32 s40, v179
	v_readfirstlane_b32 s44, v180
	v_readfirstlane_b32 s41, v181
	v_readfirstlane_b32 s37, v190
	v_readfirstlane_b32 s42, v191
	v_readfirstlane_b32 s36, v192
	v_readfirstlane_b32 s43, v193
	v_mov_b32_e32 v171, v172
	s_mov_b32 s45, 0
	s_mov_b32 s48, 0
	s_waitcnt vmcnt(3)
	ds_write_b128 v18, v[0:3]
	v_add_u32_e32 v0, 0x200, v23
	v_lshrrev_b32_e32 v0, 5, v0
	v_mad_u64_u32 v[0:1], s[16:17], v0, s96, v[8:9]
	s_waitcnt vmcnt(2)
	ds_write_b128 v0, v[4:7]
	v_add_u32_e32 v0, 0x400, v23
	v_lshrrev_b32_e32 v0, 5, v0
	v_mad_u64_u32 v[0:1], s[16:17], v0, s96, v[8:9]
	s_waitcnt vmcnt(1)
	ds_write_b128 v0, v[10:13]
	v_add_u32_e32 v0, 0x600, v23
	v_lshrrev_b32_e32 v0, 5, v0
	v_mad_u64_u32 v[0:1], s[16:17], v0, s96, v[8:9]
	s_waitcnt vmcnt(0)
	ds_write_b128 v0, v[14:17]
	v_mov_b32_e32 v16, v170
	v_mov_b32_e32 v23, v170
	v_lshlrev_b32_e32 v0, 4, v16
	v_and_b32_e32 v8, 0x1f0, v0
	v_lshl_add_u64 v[14:15], s[26:27], 0, v[8:9]
	v_lshrrev_b32_e32 v8, 5, v16
	v_lshlrev_b64 v[0:1], 14, v[8:9]
	v_lshl_add_u64 v[0:1], v[14:15], 0, v[0:1]
	v_add_u32_e32 v4, 0x200, v16
	global_load_dwordx4 v[0:3], v[0:1], off
	v_lshrrev_b32_e32 v8, 5, v4
	v_lshlrev_b64 v[4:5], 14, v[8:9]
	v_lshl_add_u64 v[4:5], v[14:15], 0, v[4:5]
	v_add_u32_e32 v8, 0x400, v16
	global_load_dwordx4 v[4:7], v[4:5], off
	v_lshrrev_b32_e32 v8, 5, v8
	v_lshlrev_b64 v[10:11], 14, v[8:9]
	v_lshl_add_u64 v[10:11], v[14:15], 0, v[10:11]
	v_add_u32_e32 v8, 0x600, v16
	global_load_dwordx4 v[10:13], v[10:11], off
	v_lshrrev_b32_e32 v8, 5, v8
	v_lshlrev_b64 v[16:17], 14, v[8:9]
	v_lshl_add_u64 v[14:15], v[14:15], 0, v[16:17]
	global_load_dwordx4 v[14:17], v[14:15], off
	s_nop 0
	v_lshlrev_b32_e32 v8, 4, v23
	v_and_b32_e32 v8, 0x1f0, v8
	v_add_u32_e32 v8, s97, v8
	v_lshrrev_b32_e32 v18, 5, v23
	v_mad_u64_u32 v[18:19], s[16:17], v18, s92, v[8:9]
	s_waitcnt vmcnt(3)
	ds_write_b128 v18, v[0:3]
	v_add_u32_e32 v0, 0x200, v23
	v_lshrrev_b32_e32 v0, 5, v0
	v_mad_u64_u32 v[0:1], s[16:17], v0, s92, v[8:9]
	s_waitcnt vmcnt(2)
	ds_write_b128 v0, v[4:7]
	v_add_u32_e32 v0, 0x400, v23
	v_lshrrev_b32_e32 v0, 5, v0
	v_mad_u64_u32 v[0:1], s[16:17], v0, s92, v[8:9]
	s_waitcnt vmcnt(1)
	ds_write_b128 v0, v[10:13]
	v_add_u32_e32 v0, 0x600, v23
	v_lshrrev_b32_e32 v0, 5, v0
	v_mad_u64_u32 v[0:1], s[16:17], v0, s92, v[8:9]
	s_waitcnt vmcnt(0)
	ds_write_b128 v0, v[14:17]
	v_lshlrev_b32_e32 v0, 9, v21
	v_and_b32_e32 v1, 48, v20
	v_lshlrev_b32_e32 v246, 4, v21
	v_xor_b32_e32 v1, v1, v246
	v_add3_u32 v195, 0, v0, v1
	v_bfe_u32 v0, v20, 2, 2
	v_or_b32_e32 v0, v194, v0
	v_lshlrev_b32_e32 v1, 3, v20
	v_mul_u32_u24_e32 v0, 0x220, v0
	v_and_b32_e32 v1, 24, v1
	v_mov_b32_e32 v10, v9
	v_mov_b32_e32 v11, v9
	v_add3_u32 v173, s97, v0, v1
	v_add_u32_e32 v0, s4, v21
	v_mov_b32_e32 v8, v9
	v_mov_b64_e32 v[44:45], v[10:11]
	v_mov_b64_e32 v[48:49], v[10:11]
	v_mov_b64_e32 v[52:53], v[10:11]
	v_mov_b64_e32 v[56:57], v[10:11]
	v_mov_b64_e32 v[60:61], v[10:11]
	v_mov_b64_e32 v[64:65], v[10:11]
	v_mov_b64_e32 v[68:69], v[10:11]
	v_mov_b64_e32 v[72:73], v[10:11]
	v_mov_b64_e32 v[40:41], v[10:11]
	v_mov_b64_e32 v[36:37], v[10:11]
	v_mov_b64_e32 v[32:33], v[10:11]
	v_mov_b64_e32 v[28:29], v[10:11]
	v_mov_b64_e32 v[24:25], v[10:11]
	v_mov_b64_e32 v[20:21], v[10:11]
	v_mov_b64_e32 v[16:17], v[10:11]
	s_lshr_b32 s17, s5, 6
	v_mov_b64_e32 v[42:43], v[8:9]
	v_mov_b64_e32 v[46:47], v[8:9]
	v_mov_b64_e32 v[50:51], v[8:9]
	v_mov_b64_e32 v[54:55], v[8:9]
	v_mov_b64_e32 v[58:59], v[8:9]
	v_mov_b64_e32 v[62:63], v[8:9]
	v_mov_b64_e32 v[66:67], v[8:9]
	v_mov_b64_e32 v[70:71], v[8:9]
	v_mov_b64_e32 v[38:39], v[8:9]
	v_mov_b64_e32 v[34:35], v[8:9]
	v_mov_b64_e32 v[30:31], v[8:9]
	v_mov_b64_e32 v[26:27], v[8:9]
	v_mov_b64_e32 v[22:23], v[8:9]
	v_mov_b64_e32 v[18:19], v[8:9]
	v_mov_b64_e32 v[14:15], v[8:9]
	v_mov_b64_e32 v[12:13], v[10:11]
	s_or_b32 s16, s4, 15
	s_add_i32 s17, s17, -1
	v_sub_u32_e32 v196, v0, v194
	v_mov_b64_e32 v[10:11], v[8:9]
	s_waitcnt lgkmcnt(0)
	s_barrier
	s_branch .LBB0_865

.LBB0_864:
	s_lshl_b32 s4, s49, 6
	s_nop 1
	v_mov_b32_e32 v1, v170
	s_xor_b32 s49, s4, 64
	s_mul_i32 s4, s49, 0x210
	v_lshlrev_b32_e32 v0, 4, v1
	s_add_i32 s4, s4, 0
	v_and_b32_e32 v0, 0x1f0, v0
	v_lshrrev_b32_e32 v246, 1, v1
	v_and_b32_e32 v246, 0xf0, v246
	v_xor_b32_e32 v0, v0, v246
	v_add_u32_e32 v0, s4, v0
	v_lshrrev_b32_e32 v2, 5, v1
	v_mad_u64_u32 v[2:3], s[4:5], v2, s96, v[0:1]
	s_waitcnt vmcnt(7)
	ds_write_b128 v2, v[110:113]
	v_add_u32_e32 v2, 0x200, v1
	v_lshrrev_b32_e32 v2, 5, v2
	v_mad_u64_u32 v[2:3], s[4:5], v2, s96, v[0:1]
	s_waitcnt vmcnt(6)
	ds_write_b128 v2, v[106:109]
	v_add_u32_e32 v2, 0x400, v1
	v_lshrrev_b32_e32 v2, 5, v2
	v_mad_u64_u32 v[2:3], s[4:5], v2, s96, v[0:1]
	v_add_u32_e32 v1, 0x600, v1
	v_lshrrev_b32_e32 v1, 5, v1
	v_mad_u64_u32 v[0:1], s[4:5], v1, s96, v[0:1]
	v_mov_b32_e32 v1, v170
	s_mulk_i32 s49, 0x220
	s_waitcnt vmcnt(5)
	ds_write_b128 v2, v[118:121]
	s_waitcnt vmcnt(4)
	ds_write_b128 v0, v[114:117]
	s_add_i32 s4, s49, 0
	v_lshlrev_b32_e32 v0, 4, v1
	s_add_i32 s4, s4, 0x10800
	v_and_b32_e32 v0, 0x1f0, v0
	v_add_u32_e32 v0, s4, v0
	v_lshrrev_b32_e32 v2, 5, v1
	v_mad_u64_u32 v[2:3], s[4:5], v2, s92, v[0:1]
	s_waitcnt vmcnt(3)
	ds_write_b128 v2, v[126:129]
	v_add_u32_e32 v2, 0x200, v1
	v_lshrrev_b32_e32 v2, 5, v2
	v_mad_u64_u32 v[2:3], s[4:5], v2, s92, v[0:1]
	s_waitcnt vmcnt(2)
	ds_write_b128 v2, v[122:125]
	v_add_u32_e32 v2, 0x400, v1
	v_lshrrev_b32_e32 v2, 5, v2
	v_mad_u64_u32 v[2:3], s[4:5], v2, s92, v[0:1]
	v_add_u32_e32 v1, 0x600, v1
	s_add_i32 s48, s48, 1
	v_lshrrev_b32_e32 v1, 5, v1
	s_add_i32 s45, s45, 64
	v_mad_u64_u32 v[0:1], s[4:5], v1, s92, v[0:1]
	s_cmp_eq_u32 s17, s48
	v_subrev_u32_e32 v196, 64, v196
	s_waitcnt vmcnt(1)
	ds_write_b128 v2, v[134:137]
	s_waitcnt vmcnt(0)
	ds_write_b128 v0, v[130:133]
	s_waitcnt lgkmcnt(0)
	s_barrier
	s_cbranch_scc1 .LBB0_870
.LBB0_865:
	v_mov_b32_e32 v6, v170
	s_and_b32 s49, s48, 1
	v_lshlrev_b32_e32 v0, 4, v6
	v_and_b32_e32 v8, 0x1f0, v0
	v_lshrrev_b32_e32 v2, 5, v6
	v_add_u32_e32 v4, 0x200, v6
	v_lshl_add_u64 v[0:1], s[24:25], 0, v[8:9]
	v_add3_u32 v8, s45, v2, 64
	v_lshrrev_b32_e32 v4, 5, v4
	v_lshlrev_b64 v[2:3], 14, v[8:9]
	v_add3_u32 v8, s45, v4, 64
	v_lshl_add_u64 v[2:3], v[0:1], 0, v[2:3]
	v_lshlrev_b64 v[4:5], 14, v[8:9]
	v_lshl_add_u64 v[4:5], v[0:1], 0, v[4:5]
	global_load_dwordx4 v[110:113], v[2:3], off
	global_load_dwordx4 v[106:109], v[4:5], off
	v_add_u32_e32 v2, 0x400, v6
	v_lshrrev_b32_e32 v2, 5, v2
	v_add_u32_e32 v4, 0x600, v6
	v_add3_u32 v8, s45, v2, 64
	v_lshrrev_b32_e32 v4, 5, v4
	v_lshlrev_b64 v[2:3], 14, v[8:9]
	v_add3_u32 v8, s45, v4, 64
	v_lshlrev_b64 v[4:5], 14, v[8:9]
	v_lshl_add_u64 v[2:3], v[0:1], 0, v[2:3]
	v_lshl_add_u64 v[0:1], v[0:1], 0, v[4:5]
	v_mov_b32_e32 v6, v170
	global_load_dwordx4 v[118:121], v[2:3], off
	global_load_dwordx4 v[114:117], v[0:1], off
	s_cmp_gt_i32 s45, s16
	v_lshlrev_b32_e32 v0, 4, v6
	v_and_b32_e32 v8, 0x1f0, v0
	v_lshrrev_b32_e32 v2, 5, v6
	v_add_u32_e32 v4, 0x200, v6
	v_lshl_add_u64 v[0:1], s[26:27], 0, v[8:9]
	v_add3_u32 v8, s45, v2, 64
	v_lshrrev_b32_e32 v4, 5, v4
	v_lshlrev_b64 v[2:3], 14, v[8:9]
	v_add3_u32 v8, s45, v4, 64
	v_lshl_add_u64 v[2:3], v[0:1], 0, v[2:3]
	v_lshlrev_b64 v[4:5], 14, v[8:9]
	v_lshl_add_u64 v[4:5], v[0:1], 0, v[4:5]
	global_load_dwordx4 v[126:129], v[2:3], off
	global_load_dwordx4 v[122:125], v[4:5], off
	v_add_u32_e32 v2, 0x400, v6
	v_lshrrev_b32_e32 v2, 5, v2
	v_add_u32_e32 v4, 0x600, v6
	v_add3_u32 v8, s45, v2, 64
	v_lshrrev_b32_e32 v4, 5, v4
	v_lshlrev_b64 v[2:3], 14, v[8:9]
	v_add3_u32 v8, s45, v4, 64
	v_lshl_add_u64 v[2:3], v[0:1], 0, v[2:3]
	v_lshlrev_b64 v[4:5], 14, v[8:9]
	v_lshl_add_u64 v[0:1], v[0:1], 0, v[4:5]
	global_load_dwordx4 v[134:137], v[2:3], off
	global_load_dwordx4 v[130:133], v[0:1], off
	s_cbranch_scc1 .LBB0_864
	s_mul_i32 s4, s49, 0x8400
	v_add_u32_e32 v8, s4, v195
	v_xor_b32_e32 v246, 64, v8
	v_xor_b32_e32 v247, 0x80, v8
	v_xor_b32_e32 v248, 0xc0, v8
	ds_read_b128 v[0:3], v8
	ds_read_b128 v[4:7], v8 offset:8192
	ds_read_b128 v[174:177], v8 offset:16384
	ds_read_b128 v[198:201], v8 offset:24576
	ds_read_b128 v[202:205], v246
	ds_read_b128 v[206:209], v246 offset:8192
	ds_read_b128 v[210:213], v246 offset:16384
	ds_read_b128 v[214:217], v246 offset:24576
	ds_read_b128 v[218:221], v247
	ds_read_b128 v[226:229], v247 offset:8192
	ds_read_b128 v[230:233], v247 offset:16384
	ds_read_b128 v[234:237], v247 offset:24576
	ds_read_b128 v[238:241], v248
	ds_read_b128 v[242:245], v248 offset:8192
	s_add_i32 s4, s45, 63
	s_cmp_le_u32 s4, s9
	s_waitcnt lgkmcnt(13)
	v_mfma_f32_16x16x32_bf16 v[150:153], v[0:3], v[102:105], 0
	ds_read_b128 v[0:3], v248 offset:16384
	s_waitcnt lgkmcnt(13)
	v_mfma_f32_16x16x32_bf16 v[146:149], v[4:7], v[102:105], 0
	ds_read_b128 v[4:7], v248 offset:24576
	s_waitcnt lgkmcnt(13)
	v_mfma_f32_16x16x32_bf16 v[142:145], v[174:177], v[102:105], 0
	ds_read_b128 v[174:177], v8 offset:256
	s_waitcnt lgkmcnt(13)
	v_mfma_f32_16x16x32_bf16 v[138:141], v[198:201], v[102:105], 0
	ds_read_b128 v[198:201], v8 offset:8448
	s_waitcnt lgkmcnt(13)
	v_mfma_f32_16x16x32_bf16 v[150:153], v[202:205], v[98:101], v[150:153]
	ds_read_b128 v[202:205], v8 offset:16640
	s_waitcnt lgkmcnt(13)
	v_mfma_f32_16x16x32_bf16 v[146:149], v[206:209], v[98:101], v[146:149]
	ds_read_b128 v[206:209], v8 offset:24832
	s_waitcnt lgkmcnt(13)
	v_mfma_f32_16x16x32_bf16 v[142:145], v[210:213], v[98:101], v[142:145]
	ds_read_b128 v[210:213], v246 offset:256
	s_waitcnt lgkmcnt(13)
	v_mfma_f32_16x16x32_bf16 v[138:141], v[214:217], v[98:101], v[138:141]
	ds_read_b128 v[214:217], v246 offset:8448
	s_waitcnt lgkmcnt(13)
	v_mfma_f32_16x16x32_bf16 v[150:153], v[218:221], v[94:97], v[150:153]
	ds_read_b128 v[218:221], v246 offset:16640
	s_waitcnt lgkmcnt(13)
	v_mfma_f32_16x16x32_bf16 v[146:149], v[226:229], v[94:97], v[146:149]
	ds_read_b128 v[226:229], v246 offset:24832
	s_waitcnt lgkmcnt(13)
	v_mfma_f32_16x16x32_bf16 v[142:145], v[230:233], v[94:97], v[142:145]
	ds_read_b128 v[230:233], v247 offset:256
	s_waitcnt lgkmcnt(13)
	v_mfma_f32_16x16x32_bf16 v[138:141], v[234:237], v[94:97], v[138:141]
	ds_read_b128 v[234:237], v247 offset:8448
	s_waitcnt lgkmcnt(13)
	v_mfma_f32_16x16x32_bf16 v[150:153], v[238:241], v[90:93], v[150:153]
	ds_read_b128 v[238:241], v247 offset:16640
	s_waitcnt lgkmcnt(13)
	v_mfma_f32_16x16x32_bf16 v[146:149], v[242:245], v[90:93], v[146:149]
	ds_read_b128 v[242:245], v247 offset:24832
	s_waitcnt lgkmcnt(13)
	v_mfma_f32_16x16x32_bf16 v[142:145], v[0:3], v[90:93], v[142:145]
	ds_read_b128 v[0:3], v248 offset:256
	s_waitcnt lgkmcnt(13)
	v_mfma_f32_16x16x32_bf16 v[138:141], v[4:7], v[90:93], v[138:141]
	ds_read_b128 v[4:7], v248 offset:8448
	s_waitcnt lgkmcnt(13)
	v_mfma_f32_16x16x32_bf16 v[150:153], v[174:177], v[86:89], v[150:153]
	ds_read_b128 v[174:177], v248 offset:16640
	s_waitcnt lgkmcnt(13)
	v_mfma_f32_16x16x32_bf16 v[146:149], v[198:201], v[86:89], v[146:149]
	ds_read_b128 v[198:201], v248 offset:24832
	s_waitcnt lgkmcnt(13)
	v_mfma_f32_16x16x32_bf16 v[142:145], v[202:205], v[86:89], v[142:145]
	s_waitcnt lgkmcnt(12)
	v_mfma_f32_16x16x32_bf16 v[138:141], v[206:209], v[86:89], v[138:141]
	s_waitcnt lgkmcnt(11)
	v_mfma_f32_16x16x32_bf16 v[150:153], v[210:213], v[82:85], v[150:153]
	s_waitcnt lgkmcnt(10)
	v_mfma_f32_16x16x32_bf16 v[146:149], v[214:217], v[82:85], v[146:149]
	s_waitcnt lgkmcnt(9)
	v_mfma_f32_16x16x32_bf16 v[142:145], v[218:221], v[82:85], v[142:145]
	s_waitcnt lgkmcnt(8)
	v_mfma_f32_16x16x32_bf16 v[138:141], v[226:229], v[82:85], v[138:141]
	s_waitcnt lgkmcnt(7)
	v_mfma_f32_16x16x32_bf16 v[150:153], v[230:233], v[78:81], v[150:153]
	s_waitcnt lgkmcnt(6)
	v_mfma_f32_16x16x32_bf16 v[146:149], v[234:237], v[78:81], v[146:149]
	s_waitcnt lgkmcnt(5)
	v_mfma_f32_16x16x32_bf16 v[142:145], v[238:241], v[78:81], v[142:145]
	s_waitcnt lgkmcnt(4)
	v_mfma_f32_16x16x32_bf16 v[138:141], v[242:245], v[78:81], v[138:141]
	s_waitcnt lgkmcnt(3)
	v_mfma_f32_16x16x32_bf16 v[150:153], v[0:3], v[74:77], v[150:153]
	s_waitcnt lgkmcnt(2)
	v_mfma_f32_16x16x32_bf16 v[146:149], v[4:7], v[74:77], v[146:149]
	s_waitcnt lgkmcnt(1)
	v_mfma_f32_16x16x32_bf16 v[142:145], v[174:177], v[74:77], v[142:145]
	s_waitcnt lgkmcnt(0)
	v_mfma_f32_16x16x32_bf16 v[138:141], v[198:201], v[74:77], v[138:141]
	s_mov_b64 s[4:5], -1
	s_cbranch_scc0 .LBB0_868
	v_cvt_f32_i32_e32 v0, v196
	s_mov_b64 s[4:5], 0
	v_mul_f32_e32 v0, v178, v0
	v_exp_f32_e32 v8, v0
	s_nop 0
	v_mul_f32_e32 v0, s40, v8
	v_pk_mul_f32 v[2:3], s[40:41], v[0:1] op_sel_hi:[1,0]
	v_pk_mul_f32 v[0:1], s[42:43], v[0:1] op_sel_hi:[1,0]
	v_pk_mul_f32 v[2:3], v[2:3], v[150:151]
	v_pk_mul_f32 v[4:5], v[0:1], v[152:153]
	v_cvt_pk_bf16_f32 v0, v2, v3
	v_mul_f32_e32 v2, s44, v8
	v_cvt_pk_bf16_f32 v1, v4, v5
	v_pk_mul_f32 v[4:5], s[40:41], v[2:3] op_sel_hi:[1,0]
	v_pk_mul_f32 v[2:3], s[42:43], v[2:3] op_sel_hi:[1,0]
	v_pk_mul_f32 v[4:5], v[4:5], v[146:147]
	v_pk_mul_f32 v[6:7], v[2:3], v[148:149]
	v_cvt_pk_bf16_f32 v2, v4, v5
	v_mul_f32_e32 v4, s37, v8
	v_cvt_pk_bf16_f32 v3, v6, v7
	v_pk_mul_f32 v[6:7], s[40:41], v[4:5] op_sel_hi:[1,0]
	v_pk_mul_f32 v[4:5], s[42:43], v[4:5] op_sel_hi:[1,0]
	v_pk_mul_f32 v[6:7], v[6:7], v[142:143]
	v_pk_mul_f32 v[154:155], v[4:5], v[144:145]
	v_cvt_pk_bf16_f32 v4, v6, v7
	v_mul_f32_e32 v6, s36, v8
	v_cvt_pk_bf16_f32 v5, v154, v155
	v_pk_mul_f32 v[154:155], s[40:41], v[6:7] op_sel_hi:[1,0]
	v_pk_mul_f32 v[6:7], s[42:43], v[6:7] op_sel_hi:[1,0]
	v_pk_mul_f32 v[174:175], v[154:155], v[138:139]
	v_pk_mul_f32 v[176:177], v[6:7], v[140:141]

.LBB0_870:
	s_cmp_gt_i32 s45, s16
	s_cbranch_scc1 .LBB0_861
	s_and_b32 s16, s17, 1
	s_mul_i32 s4, s16, 0x8400
	v_add_u32_e32 v8, s4, v195
	v_xor_b32_e32 v246, 64, v8
	v_xor_b32_e32 v247, 0x80, v8
	v_xor_b32_e32 v248, 0xc0, v8
	ds_read_b128 v[0:3], v8
	ds_read_b128 v[4:7], v8 offset:8192
	ds_read_b128 v[106:109], v246
	ds_read_b128 v[110:113], v8 offset:16384
	ds_read_b128 v[114:117], v246 offset:8192
	ds_read_b128 v[118:121], v8 offset:24576
	ds_read_b128 v[122:125], v246 offset:16384
	s_waitcnt lgkmcnt(6)
	v_mfma_f32_16x16x32_bf16 v[0:3], v[0:3], v[102:105], 0
	ds_read_b128 v[126:129], v246 offset:24576
	s_or_b32 s4, s45, 63
	s_cmp_gt_u32 s4, s9
	s_waitcnt lgkmcnt(6)
	v_mfma_f32_16x16x32_bf16 v[4:7], v[4:7], v[102:105], 0
	s_waitcnt lgkmcnt(4)
	v_mfma_f32_16x16x32_bf16 v[110:113], v[110:113], v[102:105], 0
	s_waitcnt lgkmcnt(2)
	v_mfma_f32_16x16x32_bf16 v[102:105], v[118:121], v[102:105], 0
	v_mfma_f32_16x16x32_bf16 v[0:3], v[106:109], v[98:101], v[0:3]
	v_mfma_f32_16x16x32_bf16 v[4:7], v[114:117], v[98:101], v[4:7]
	s_waitcnt lgkmcnt(1)
	v_mfma_f32_16x16x32_bf16 v[106:109], v[122:125], v[98:101], v[110:113]
	s_nop 2
	ds_read_b128 v[110:113], v247 offset:24576
	ds_read_b128 v[114:117], v247 offset:16384
	ds_read_b128 v[118:121], v247 offset:8192
	ds_read_b128 v[122:125], v247
	s_waitcnt lgkmcnt(4)
	v_mfma_f32_16x16x32_bf16 v[98:101], v[126:129], v[98:101], v[102:105]
	s_waitcnt lgkmcnt(0)
	v_mfma_f32_16x16x32_bf16 v[0:3], v[122:125], v[94:97], v[0:3]
	v_mfma_f32_16x16x32_bf16 v[4:7], v[118:121], v[94:97], v[4:7]
	v_mfma_f32_16x16x32_bf16 v[102:105], v[114:117], v[94:97], v[106:109]
	s_nop 2
	ds_read_b128 v[106:109], v248
	ds_read_b128 v[114:117], v248 offset:8192
	ds_read_b128 v[118:121], v248 offset:16384
	ds_read_b128 v[122:125], v248 offset:24576
	v_mfma_f32_16x16x32_bf16 v[94:97], v[110:113], v[94:97], v[98:101]
	s_waitcnt lgkmcnt(3)
	v_mfma_f32_16x16x32_bf16 v[0:3], v[106:109], v[90:93], v[0:3]
	s_waitcnt lgkmcnt(2)
	v_mfma_f32_16x16x32_bf16 v[4:7], v[114:117], v[90:93], v[4:7]
	s_waitcnt lgkmcnt(1)
	v_mfma_f32_16x16x32_bf16 v[98:101], v[118:121], v[90:93], v[102:105]
	s_nop 2
	ds_read_b128 v[102:105], v8 offset:24832
	ds_read_b128 v[106:109], v8 offset:16640
	ds_read_b128 v[110:113], v8 offset:8448
	ds_read_b128 v[114:117], v8 offset:256
	s_waitcnt lgkmcnt(4)
	v_mfma_f32_16x16x32_bf16 v[90:93], v[122:125], v[90:93], v[94:97]
	s_waitcnt lgkmcnt(0)
	v_mfma_f32_16x16x32_bf16 v[0:3], v[114:117], v[86:89], v[0:3]
	v_mfma_f32_16x16x32_bf16 v[4:7], v[110:113], v[86:89], v[4:7]
	v_mfma_f32_16x16x32_bf16 v[94:97], v[106:109], v[86:89], v[98:101]
	s_nop 2
	ds_read_b128 v[98:101], v246 offset:256
	ds_read_b128 v[106:109], v246 offset:8448
	ds_read_b128 v[110:113], v246 offset:16640
	ds_read_b128 v[114:117], v246 offset:24832
	v_mfma_f32_16x16x32_bf16 v[86:89], v[102:105], v[86:89], v[90:93]
	s_waitcnt lgkmcnt(3)
	v_mfma_f32_16x16x32_bf16 v[0:3], v[98:101], v[82:85], v[0:3]
	s_waitcnt lgkmcnt(2)
	v_mfma_f32_16x16x32_bf16 v[4:7], v[106:109], v[82:85], v[4:7]
	s_waitcnt lgkmcnt(1)
	v_mfma_f32_16x16x32_bf16 v[90:93], v[110:113], v[82:85], v[94:97]
	s_nop 2
	ds_read_b128 v[94:97], v247 offset:24832
	ds_read_b128 v[98:101], v247 offset:16640
	ds_read_b128 v[102:105], v247 offset:8448
	ds_read_b128 v[106:109], v247 offset:256
	s_waitcnt lgkmcnt(4)
	v_mfma_f32_16x16x32_bf16 v[82:85], v[114:117], v[82:85], v[86:89]
	s_waitcnt lgkmcnt(0)
	v_mfma_f32_16x16x32_bf16 v[0:3], v[106:109], v[78:81], v[0:3]
	v_mfma_f32_16x16x32_bf16 v[4:7], v[102:105], v[78:81], v[4:7]
	v_mfma_f32_16x16x32_bf16 v[90:93], v[98:101], v[78:81], v[90:93]
	ds_read_b128 v[86:89], v248 offset:256
	ds_read_b128 v[98:101], v248 offset:8448
	ds_read_b128 v[102:105], v248 offset:16640
	ds_read_b128 v[106:109], v248 offset:24832
	v_mfma_f32_16x16x32_bf16 v[94:97], v[94:97], v[78:81], v[82:85]
	s_waitcnt lgkmcnt(3)
	v_mfma_f32_16x16x32_bf16 v[86:89], v[86:89], v[74:77], v[0:3]
	s_waitcnt lgkmcnt(2)
	v_mfma_f32_16x16x32_bf16 v[82:85], v[98:101], v[74:77], v[4:7]
	s_waitcnt lgkmcnt(1)
	v_mfma_f32_16x16x32_bf16 v[78:81], v[102:105], v[74:77], v[90:93]
	s_waitcnt lgkmcnt(0)
	v_mfma_f32_16x16x32_bf16 v[74:77], v[106:109], v[74:77], v[94:97]
	v_or_b32_e32 v8, s45, v194
	s_nop 1
	v_sub_u32_e32 v94, v172, v8
	s_mov_b64 s[4:5], -1
	s_cbranch_scc1 .LBB0_873
	v_cvt_f32_i32_e32 v0, v94
	s_mov_b64 s[4:5], 0
	v_mul_f32_e32 v0, v178, v0
	v_exp_f32_e32 v92, v0
	s_nop 0
	v_mul_f32_e32 v0, s40, v92
	v_pk_mul_f32 v[2:3], s[40:41], v[0:1] op_sel_hi:[1,0]
	v_pk_mul_f32 v[0:1], s[42:43], v[0:1] op_sel_hi:[1,0]
	v_pk_mul_f32 v[2:3], v[2:3], v[86:87]
	v_pk_mul_f32 v[4:5], v[0:1], v[88:89]
	v_cvt_pk_bf16_f32 v0, v2, v3
	v_mul_f32_e32 v2, s44, v92
	v_cvt_pk_bf16_f32 v1, v4, v5
	v_pk_mul_f32 v[4:5], s[40:41], v[2:3] op_sel_hi:[1,0]
	v_pk_mul_f32 v[2:3], s[42:43], v[2:3] op_sel_hi:[1,0]
	v_pk_mul_f32 v[4:5], v[4:5], v[82:83]
	v_pk_mul_f32 v[6:7], v[2:3], v[84:85]
	v_cvt_pk_bf16_f32 v2, v4, v5
	v_mul_f32_e32 v4, s37, v92
	v_cvt_pk_bf16_f32 v3, v6, v7
	v_pk_mul_f32 v[6:7], s[40:41], v[4:5] op_sel_hi:[1,0]
	v_pk_mul_f32 v[4:5], s[42:43], v[4:5] op_sel_hi:[1,0]
	v_pk_mul_f32 v[6:7], v[6:7], v[78:79]
	v_pk_mul_f32 v[90:91], v[4:5], v[80:81]
	v_cvt_pk_bf16_f32 v4, v6, v7
	v_mul_f32_e32 v6, s36, v92
	v_cvt_pk_bf16_f32 v5, v90, v91
	v_pk_mul_f32 v[90:91], s[40:41], v[6:7] op_sel_hi:[1,0]
	v_pk_mul_f32 v[6:7], s[42:43], v[6:7] op_sel_hi:[1,0]
	v_pk_mul_f32 v[90:91], v[90:91], v[74:75]
	v_pk_mul_f32 v[92:93], v[6:7], v[76:77]
